# norm phases: bf16 row stores (8 bytes per lane) write-through as well; no L2 write-back at the barriers after the norm phases
# baseline (speedup 1.0000x reference)
.LBB0_333:
	global_load_dwordx4 v[12:15], v1, s[16:17]
	global_load_dwordx4 v[16:19], v1, s[16:17] offset:1024
	global_load_dwordx4 v[20:23], v1, s[16:17] offset:2048
	global_load_dwordx4 v[24:27], v1, s[16:17] offset:3072
	s_lshr_b32 s2, s2, 10
	s_mulk_i32 s2, 0x1800
	s_addk_i32 s2, 0x1800
	s_and_b64 s[14:15], s[14:15], exec
	s_cselect_b32 s2, 0, s2
	s_lshl_b64 s[14:15], s[2:3], 2
	v_lshl_add_u64 v[40:41], v[4:5], 0, s[14:15]
	global_load_dwordx4 v[28:31], v[40:41], off
	global_load_dwordx4 v[32:35], v[2:3], off
	v_lshl_add_u64 v[42:43], v[6:7], 0, s[14:15]
	global_load_dwordx4 v[36:39], v[42:43], off
	s_lshl_b64 s[12:13], s[12:13], 11
	s_add_u32 s4, s4, s6
	s_addc_u32 s5, s5, s7
	s_add_u32 s8, s8, s10
	s_addc_u32 s9, s9, s11
	s_cmpk_lt_i32 s4, 0x1800
	s_waitcnt vmcnt(6)
	v_mov_b32_e32 v46, v13
	s_waitcnt vmcnt(5)
	v_mov_b32_e32 v47, v17
	v_mov_b32_e32 v44, v12
	v_mov_b32_e32 v45, v16
	s_waitcnt vmcnt(4)
	v_mov_b32_e32 v58, v21
	s_waitcnt vmcnt(3)
	v_mov_b32_e32 v59, v25
	v_pk_mul_f32 v[46:47], v[46:47], v[46:47]
	v_mov_b32_e32 v48, v14
	v_mov_b32_e32 v49, v18
	v_mov_b32_e32 v56, v20
	v_mov_b32_e32 v57, v24
	v_pk_mul_f32 v[58:59], v[58:59], v[58:59]
	v_pk_fma_f32 v[44:45], v[44:45], v[44:45], v[46:47]
	v_mov_b32_e32 v50, v15
	v_mov_b32_e32 v51, v19
	v_mov_b32_e32 v54, v22
	v_mov_b32_e32 v55, v26
	v_pk_fma_f32 v[46:47], v[56:57], v[56:57], v[58:59]
	v_pk_fma_f32 v[44:45], v[48:49], v[48:49], v[44:45]
	v_mov_b32_e32 v52, v23
	v_mov_b32_e32 v53, v27
	v_pk_fma_f32 v[46:47], v[54:55], v[54:55], v[46:47]
	v_pk_fma_f32 v[44:45], v[50:51], v[50:51], v[44:45]
	v_pk_fma_f32 v[46:47], v[52:53], v[52:53], v[46:47]
	v_add_f32_e32 v11, v44, v45
	v_add_f32_e32 v11, v11, v46
	v_add_f32_e32 v11, v11, v47
	s_waitcnt vmcnt(2)
	v_pk_add_f32 v[28:29], v[28:29], 1.0 op_sel_hi:[1,0]
	v_pk_add_f32 v[30:31], v[30:31], 1.0 op_sel_hi:[1,0]
	v_add_f32_dpp v11, v11, v11 quad_perm:[1,0,3,2] row_mask:0xf bank_mask:0xf bound_ctrl:1
	s_nop 1
	v_add_f32_dpp v11, v11, v11 quad_perm:[2,3,0,1] row_mask:0xf bank_mask:0xf bound_ctrl:1
	s_nop 1
	v_add_f32_dpp v11, v11, v11 row_half_mirror row_mask:0xf bank_mask:0xf bound_ctrl:1
	s_nop 1
	v_add_f32_dpp v11, v11, v11 row_mirror row_mask:0xf bank_mask:0xf bound_ctrl:1
	s_nop 0
	v_readlane_b32 s2, v11, 16
	v_readlane_b32 s16, v11, 48
	v_readlane_b32 s14, v11, 0
	v_readlane_b32 s15, v11, 32
	v_mov_b32_e32 v44, s2
	v_mov_b32_e32 v45, s16
	v_pk_add_f32 v[44:45], s[14:15], v[44:45]
	s_nop 0
	v_add_f32_e32 v11, v44, v45
	v_fmamk_f32 v11, v11, 0x3a800000, v10
	v_mul_f32_e32 v44, 0x4b800000, v11
	v_cmp_gt_f32_e32 vcc, s22, v11
	s_nop 1
	v_cndmask_b32_e32 v11, v11, v44, vcc
	v_rsq_f32_e32 v11, v11
	v_lshl_add_u64 v[44:45], v[8:9], 0, s[12:13]
	v_mul_f32_e32 v46, 0x45800000, v11
	v_cndmask_b32_e32 v46, v11, v46, vcc
	v_pk_mul_f32 v[12:13], v[12:13], v[46:47] op_sel_hi:[1,0]
	v_pk_mul_f32 v[14:15], v[14:15], v[46:47] op_sel_hi:[1,0]
	s_waitcnt vmcnt(1)
	v_pk_mul_f32 v[12:13], v[32:33], v[12:13]
	v_pk_mul_f32 v[14:15], v[34:35], v[14:15]
	s_waitcnt vmcnt(0)
	v_pk_fma_f32 v[12:13], v[28:29], v[12:13], v[36:37]
	v_pk_fma_f32 v[14:15], v[30:31], v[14:15], v[38:39]
	v_cvt_pk_bf16_f32 v12, v12, v13
	v_cvt_pk_bf16_f32 v13, v14, v15
	global_store_dwordx2 v[44:45], v[12:13], off sc1
	global_load_dwordx4 v[12:15], v[2:3], off offset:1024
	s_nop 0
	global_load_dwordx4 v[28:31], v[40:41], off offset:1024
	global_load_dwordx4 v[32:35], v[42:43], off offset:1024
	v_pk_mul_f32 v[16:17], v[16:17], v[46:47] op_sel_hi:[1,0]
	v_pk_mul_f32 v[18:19], v[18:19], v[46:47] op_sel_hi:[1,0]
	v_pk_mul_f32 v[20:21], v[20:21], v[46:47] op_sel_hi:[1,0]
	v_pk_mul_f32 v[22:23], v[22:23], v[46:47] op_sel_hi:[1,0]
	v_pk_mul_f32 v[24:25], v[24:25], v[46:47] op_sel_hi:[1,0]
	v_pk_mul_f32 v[26:27], v[26:27], v[46:47] op_sel_hi:[1,0]
	s_waitcnt vmcnt(2)
	v_pk_mul_f32 v[12:13], v[12:13], v[16:17]
	s_waitcnt vmcnt(1)
	v_pk_add_f32 v[16:17], v[28:29], 1.0 op_sel_hi:[1,0]
	v_pk_mul_f32 v[14:15], v[14:15], v[18:19]
	v_pk_add_f32 v[18:19], v[30:31], 1.0 op_sel_hi:[1,0]
	s_waitcnt vmcnt(0)
	v_pk_fma_f32 v[12:13], v[16:17], v[12:13], v[32:33]
	v_pk_fma_f32 v[14:15], v[18:19], v[14:15], v[34:35]
	v_cvt_pk_bf16_f32 v12, v12, v13
	v_cvt_pk_bf16_f32 v13, v14, v15
	global_store_dwordx2 v[44:45], v[12:13], off offset:512 sc1
	global_load_dwordx4 v[12:15], v[2:3], off offset:2048
	s_nop 0
	global_load_dwordx4 v[16:19], v[40:41], off offset:2048
	global_load_dwordx4 v[28:31], v[42:43], off offset:2048
	s_waitcnt vmcnt(2)
	v_pk_mul_f32 v[12:13], v[12:13], v[20:21]
	s_waitcnt vmcnt(1)
	v_pk_add_f32 v[16:17], v[16:17], 1.0 op_sel_hi:[1,0]
	v_pk_mul_f32 v[14:15], v[14:15], v[22:23]
	v_pk_add_f32 v[18:19], v[18:19], 1.0 op_sel_hi:[1,0]
	s_waitcnt vmcnt(0)
	v_pk_fma_f32 v[12:13], v[12:13], v[16:17], v[28:29]
	v_pk_fma_f32 v[14:15], v[14:15], v[18:19], v[30:31]
	v_cvt_pk_bf16_f32 v12, v12, v13
	v_cvt_pk_bf16_f32 v13, v14, v15
	global_store_dwordx2 v[44:45], v[12:13], off offset:1024 sc1
	global_load_dwordx4 v[12:15], v[2:3], off offset:3072
	s_nop 0
	global_load_dwordx4 v[16:19], v[40:41], off offset:3072
	global_load_dwordx4 v[20:23], v[42:43], off offset:3072
	s_waitcnt vmcnt(2)
	v_pk_mul_f32 v[12:13], v[24:25], v[12:13]
	s_waitcnt vmcnt(1)
	v_pk_add_f32 v[16:17], v[16:17], 1.0 op_sel_hi:[1,0]
	v_pk_mul_f32 v[14:15], v[26:27], v[14:15]
	v_pk_add_f32 v[18:19], v[18:19], 1.0 op_sel_hi:[1,0]
	s_waitcnt vmcnt(0)
	v_pk_fma_f32 v[12:13], v[12:13], v[16:17], v[20:21]
	v_pk_fma_f32 v[14:15], v[14:15], v[18:19], v[22:23]
	v_cvt_pk_bf16_f32 v12, v12, v13
	v_cvt_pk_bf16_f32 v13, v14, v15
	global_store_dwordx2 v[44:45], v[12:13], off offset:1536 sc1
	s_cbranch_scc0 .LBB0_338

.LBB0_1342:
	s_lshr_b32 s2, s2, 10
	s_mulk_i32 s2, 0x1800
	s_addk_i32 s2, 0x1800
	s_and_b64 s[12:13], s[12:13], exec
	s_cselect_b32 s2, 0, s2
	s_lshl_b64 s[12:13], s[18:19], 11
	v_lshl_add_u64 v[40:41], v[8:9], 0, s[12:13]
	global_load_dwordx2 v[28:29], v[40:41], off
	v_lshl_add_u64 v[42:43], v[10:11], 0, s[12:13]
	s_lshl_b64 s[16:17], s[2:3], 2
	global_load_dwordx2 v[30:31], v[42:43], off
	global_load_dwordx4 v[2:5], v1, s[14:15]
	v_lshl_add_u64 v[44:45], v[12:13], 0, s[16:17]
	global_load_dwordx4 v[24:27], v[44:45], off
	s_lshl_b64 s[18:19], s[18:19], 12
	v_lshl_add_u64 v[46:47], v[14:15], 0, s[18:19]
	v_lshl_add_u64 v[52:53], v[16:17], 0, s[16:17]
	s_add_u32 s4, s4, s6
	s_addc_u32 s5, s5, s7
	s_add_u32 s8, s8, s10
	s_addc_u32 s9, s9, s11
	s_cmpk_lt_i32 s4, 0x1800
	s_waitcnt vmcnt(3)
	v_lshlrev_b32_e32 v32, 16, v28
	v_and_b32_e32 v33, 0xffff0000, v28
	s_waitcnt vmcnt(2)
	v_lshlrev_b32_e32 v34, 16, v30
	v_and_b32_e32 v35, 0xffff0000, v30
	v_lshlrev_b32_e32 v28, 16, v29
	v_and_b32_e32 v29, 0xffff0000, v29
	v_lshlrev_b32_e32 v30, 16, v31
	v_and_b32_e32 v31, 0xffff0000, v31
	v_pk_add_f32 v[32:33], v[32:33], v[34:35]
	v_pk_add_f32 v[28:29], v[28:29], v[30:31]
	s_waitcnt vmcnt(0)
	v_pk_fma_f32 v[2:3], v[24:25], v[32:33], v[2:3]
	v_pk_fma_f32 v[4:5], v[26:27], v[28:29], v[4:5]
	global_store_dwordx4 v[46:47], v[2:5], off sc1
	global_load_dwordx2 v[32:33], v[40:41], off offset:512
	global_load_dwordx2 v[34:35], v[42:43], off offset:512
	global_load_dwordx4 v[24:27], v1, s[14:15] offset:1024
	global_load_dwordx4 v[28:31], v[44:45], off offset:1024
	v_mov_b32_e32 v54, v3
	v_mov_b32_e32 v56, v4
	v_mov_b32_e32 v58, v5
	s_waitcnt vmcnt(3)
	v_lshlrev_b32_e32 v36, 16, v32
	v_and_b32_e32 v37, 0xffff0000, v32
	s_waitcnt vmcnt(2)
	v_lshlrev_b32_e32 v38, 16, v34
	v_and_b32_e32 v39, 0xffff0000, v34
	v_lshlrev_b32_e32 v32, 16, v33
	v_and_b32_e32 v33, 0xffff0000, v33
	v_lshlrev_b32_e32 v34, 16, v35
	v_and_b32_e32 v35, 0xffff0000, v35
	v_pk_add_f32 v[36:37], v[36:37], v[38:39]
	v_pk_add_f32 v[32:33], v[32:33], v[34:35]
	s_waitcnt vmcnt(0)
	v_pk_fma_f32 v[24:25], v[28:29], v[36:37], v[24:25]
	v_pk_fma_f32 v[26:27], v[30:31], v[32:33], v[26:27]
	global_store_dwordx4 v[46:47], v[24:27], off offset:1024 sc1
	global_load_dwordx2 v[36:37], v[40:41], off offset:1024
	global_load_dwordx2 v[38:39], v[42:43], off offset:1024
	global_load_dwordx4 v[28:31], v1, s[14:15] offset:2048
	global_load_dwordx4 v[32:35], v[44:45], off offset:2048
	v_mov_b32_e32 v55, v25
	v_pk_mul_f32 v[54:55], v[54:55], v[54:55]
	v_mov_b32_e32 v57, v26
	v_mov_b32_e32 v59, v27
	s_waitcnt vmcnt(3)
	v_lshlrev_b32_e32 v48, 16, v36
	v_and_b32_e32 v49, 0xffff0000, v36
	s_waitcnt vmcnt(2)
	v_lshlrev_b32_e32 v50, 16, v38
	v_and_b32_e32 v51, 0xffff0000, v38
	v_lshlrev_b32_e32 v36, 16, v37
	v_and_b32_e32 v37, 0xffff0000, v37
	v_lshlrev_b32_e32 v38, 16, v39
	v_and_b32_e32 v39, 0xffff0000, v39
	v_pk_add_f32 v[48:49], v[48:49], v[50:51]
	v_pk_add_f32 v[36:37], v[36:37], v[38:39]
	s_waitcnt vmcnt(0)
	v_pk_fma_f32 v[28:29], v[32:33], v[48:49], v[28:29]
	v_pk_fma_f32 v[30:31], v[34:35], v[36:37], v[30:31]
	global_store_dwordx4 v[46:47], v[28:31], off offset:2048 sc1
	global_load_dwordx2 v[48:49], v[40:41], off offset:1536
	global_load_dwordx2 v[50:51], v[42:43], off offset:1536
	global_load_dwordx4 v[32:35], v1, s[14:15] offset:3072
	global_load_dwordx4 v[36:39], v[44:45], off offset:3072
	s_waitcnt vmcnt(3)
	v_lshlrev_b32_e32 v40, 16, v48
	v_and_b32_e32 v41, 0xffff0000, v48
	s_waitcnt vmcnt(2)
	v_lshlrev_b32_e32 v42, 16, v50
	v_and_b32_e32 v43, 0xffff0000, v50
	v_lshlrev_b32_e32 v44, 16, v49
	v_and_b32_e32 v45, 0xffff0000, v49
	v_lshlrev_b32_e32 v48, 16, v51
	v_and_b32_e32 v49, 0xffff0000, v51
	v_pk_add_f32 v[40:41], v[40:41], v[42:43]
	v_pk_add_f32 v[42:43], v[44:45], v[48:49]
	s_waitcnt vmcnt(0)
	v_pk_fma_f32 v[32:33], v[36:37], v[40:41], v[32:33]
	v_pk_fma_f32 v[34:35], v[38:39], v[42:43], v[34:35]
	global_store_dwordx4 v[46:47], v[32:35], off offset:3072 sc1
	global_load_dwordx4 v[36:39], v[6:7], off
	global_load_dwordx4 v[40:43], v[52:53], off
	v_lshl_add_u64 v[48:49], v[18:19], 0, s[16:17]
	global_load_dwordx4 v[44:47], v[48:49], off
	v_mov_b32_e32 v50, v2
	v_mov_b32_e32 v51, v24
	v_pk_fma_f32 v[50:51], v[50:51], v[50:51], v[54:55]
	v_mov_b32_e32 v54, v30
	v_pk_fma_f32 v[50:51], v[56:57], v[56:57], v[50:51]
	v_mov_b32_e32 v56, v28
	v_pk_fma_f32 v[50:51], v[58:59], v[58:59], v[50:51]
	v_mov_b32_e32 v58, v29
	v_mov_b32_e32 v59, v33
	v_mov_b32_e32 v57, v32
	v_pk_mul_f32 v[58:59], v[58:59], v[58:59]
	v_mov_b32_e32 v55, v34
	v_pk_fma_f32 v[56:57], v[56:57], v[56:57], v[58:59]
	v_add_f32_e32 v23, v50, v51
	v_mov_b32_e32 v50, v31
	v_mov_b32_e32 v51, v35
	v_pk_fma_f32 v[54:55], v[54:55], v[54:55], v[56:57]
	s_nop 0
	v_pk_fma_f32 v[50:51], v[50:51], v[50:51], v[54:55]
	s_nop 0
	v_add_f32_e32 v23, v23, v50
	v_add_f32_e32 v23, v23, v51
	s_nop 1
	v_add_f32_dpp v23, v23, v23 quad_perm:[1,0,3,2] row_mask:0xf bank_mask:0xf bound_ctrl:1
	s_nop 1
	v_add_f32_dpp v23, v23, v23 quad_perm:[2,3,0,1] row_mask:0xf bank_mask:0xf bound_ctrl:1
	s_nop 1
	v_add_f32_dpp v23, v23, v23 row_half_mirror row_mask:0xf bank_mask:0xf bound_ctrl:1
	s_nop 1
	v_add_f32_dpp v23, v23, v23 row_mirror row_mask:0xf bank_mask:0xf bound_ctrl:1
	s_nop 0
	v_readlane_b32 s2, v23, 16
	v_readlane_b32 s16, v23, 48
	v_readlane_b32 s14, v23, 0
	v_readlane_b32 s15, v23, 32
	v_mov_b32_e32 v50, s2
	v_mov_b32_e32 v51, s16
	v_pk_add_f32 v[50:51], s[14:15], v[50:51]
	s_nop 0
	v_add_f32_e32 v23, v50, v51
	v_fmamk_f32 v23, v23, 0x3a800000, v22
	v_mul_f32_e32 v50, 0x4b800000, v23
	v_cmp_gt_f32_e32 vcc, s22, v23
	s_nop 1
	v_cndmask_b32_e32 v23, v23, v50, vcc
	v_rsq_f32_e32 v23, v23
	v_lshl_add_u64 v[50:51], v[20:21], 0, s[12:13]
	v_mul_f32_e32 v54, 0x45800000, v23
	v_cndmask_b32_e32 v54, v23, v54, vcc
	v_pk_mul_f32 v[2:3], v[2:3], v[54:55] op_sel_hi:[1,0]
	v_pk_mul_f32 v[4:5], v[4:5], v[54:55] op_sel_hi:[1,0]
	v_pk_mul_f32 v[24:25], v[24:25], v[54:55] op_sel_hi:[1,0]
	v_pk_mul_f32 v[26:27], v[26:27], v[54:55] op_sel_hi:[1,0]
	v_pk_mul_f32 v[28:29], v[28:29], v[54:55] op_sel_hi:[1,0]
	v_pk_mul_f32 v[30:31], v[30:31], v[54:55] op_sel_hi:[1,0]
	v_pk_mul_f32 v[32:33], v[32:33], v[54:55] op_sel_hi:[1,0]
	v_pk_mul_f32 v[34:35], v[34:35], v[54:55] op_sel_hi:[1,0]
	s_waitcnt vmcnt(2)
	v_pk_mul_f32 v[2:3], v[36:37], v[2:3]
	s_waitcnt vmcnt(1)
	v_pk_add_f32 v[36:37], v[40:41], 1.0 op_sel_hi:[1,0]
	v_pk_mul_f32 v[4:5], v[38:39], v[4:5]
	v_pk_add_f32 v[38:39], v[42:43], 1.0 op_sel_hi:[1,0]
	s_waitcnt vmcnt(0)
	v_pk_fma_f32 v[2:3], v[36:37], v[2:3], v[44:45]
	v_pk_fma_f32 v[4:5], v[38:39], v[4:5], v[46:47]
	v_cvt_pk_bf16_f32 v2, v2, v3
	v_cvt_pk_bf16_f32 v3, v4, v5
	global_store_dwordx2 v[50:51], v[2:3], off sc1
	global_load_dwordx4 v[2:5], v[6:7], off offset:1024
	s_nop 0
	global_load_dwordx4 v[36:39], v[52:53], off offset:1024
	global_load_dwordx4 v[40:43], v[48:49], off offset:1024
	s_waitcnt vmcnt(2)
	v_pk_mul_f32 v[2:3], v[2:3], v[24:25]
	s_waitcnt vmcnt(1)
	v_pk_add_f32 v[24:25], v[36:37], 1.0 op_sel_hi:[1,0]
	v_pk_mul_f32 v[4:5], v[4:5], v[26:27]
	v_pk_add_f32 v[26:27], v[38:39], 1.0 op_sel_hi:[1,0]
	s_waitcnt vmcnt(0)
	v_pk_fma_f32 v[2:3], v[24:25], v[2:3], v[40:41]
	v_pk_fma_f32 v[4:5], v[26:27], v[4:5], v[42:43]
	v_cvt_pk_bf16_f32 v2, v2, v3
	v_cvt_pk_bf16_f32 v3, v4, v5
	global_store_dwordx2 v[50:51], v[2:3], off offset:512 sc1
	global_load_dwordx4 v[2:5], v[6:7], off offset:2048
	s_nop 0
	global_load_dwordx4 v[24:27], v[52:53], off offset:2048
	global_load_dwordx4 v[36:39], v[48:49], off offset:2048
	s_waitcnt vmcnt(2)
	v_pk_mul_f32 v[2:3], v[2:3], v[28:29]
	s_waitcnt vmcnt(1)
	v_pk_add_f32 v[24:25], v[24:25], 1.0 op_sel_hi:[1,0]
	v_pk_mul_f32 v[4:5], v[4:5], v[30:31]
	v_pk_add_f32 v[26:27], v[26:27], 1.0 op_sel_hi:[1,0]
	s_waitcnt vmcnt(0)
	v_pk_fma_f32 v[2:3], v[2:3], v[24:25], v[36:37]
	v_pk_fma_f32 v[4:5], v[4:5], v[26:27], v[38:39]
	v_cvt_pk_bf16_f32 v2, v2, v3
	v_cvt_pk_bf16_f32 v3, v4, v5
	global_store_dwordx2 v[50:51], v[2:3], off offset:1024 sc1
	global_load_dwordx4 v[2:5], v[6:7], off offset:3072
	s_nop 0
	global_load_dwordx4 v[24:27], v[52:53], off offset:3072
	global_load_dwordx4 v[28:31], v[48:49], off offset:3072
	s_waitcnt vmcnt(2)
	v_pk_mul_f32 v[2:3], v[32:33], v[2:3]
	s_waitcnt vmcnt(1)
	v_pk_add_f32 v[24:25], v[24:25], 1.0 op_sel_hi:[1,0]
	v_pk_mul_f32 v[4:5], v[34:35], v[4:5]
	v_pk_add_f32 v[26:27], v[26:27], 1.0 op_sel_hi:[1,0]
	s_waitcnt vmcnt(0)
	v_pk_fma_f32 v[2:3], v[2:3], v[24:25], v[28:29]
	v_pk_fma_f32 v[4:5], v[4:5], v[26:27], v[30:31]
	v_cvt_pk_bf16_f32 v2, v2, v3
	v_cvt_pk_bf16_f32 v3, v4, v5
	global_store_dwordx2 v[50:51], v[2:3], off offset:1536 sc1
	s_cbranch_scc0 .LBB0_1347

.LBB0_2457:
	s_lshr_b32 s2, s2, 10
	s_mulk_i32 s2, 0x1800
	s_addk_i32 s2, 0x1800
	s_and_b64 s[12:13], s[12:13], exec
	s_cselect_b32 s2, 0, s2
	s_lshl_b64 s[12:13], s[18:19], 11
	v_lshl_add_u64 v[46:47], v[14:15], 0, s[12:13]
	global_load_dwordx2 v[34:35], v[46:47], off
	v_lshl_add_u64 v[48:49], v[16:17], 0, s[12:13]
	s_lshl_b64 s[14:15], s[2:3], 2
	global_load_dwordx2 v[36:37], v[48:49], off
	global_load_dwordx4 v[2:5], v1, s[16:17]
	v_lshl_add_u64 v[50:51], v[18:19], 0, s[14:15]
	global_load_dwordx4 v[30:33], v[50:51], off
	s_lshl_b64 s[18:19], s[18:19], 12
	v_lshl_add_u64 v[52:53], v[20:21], 0, s[18:19]
	v_lshl_add_u64 v[58:59], v[22:23], 0, s[14:15]
	s_add_u32 s4, s4, s6
	s_addc_u32 s5, s5, s7
	s_add_u32 s8, s8, s10
	s_addc_u32 s9, s9, s11
	s_cmpk_lt_i32 s4, 0x1800
	s_waitcnt vmcnt(3)
	v_lshlrev_b32_e32 v38, 16, v34
	v_and_b32_e32 v39, 0xffff0000, v34
	s_waitcnt vmcnt(2)
	v_lshlrev_b32_e32 v40, 16, v36
	v_and_b32_e32 v41, 0xffff0000, v36
	v_lshlrev_b32_e32 v34, 16, v35
	v_and_b32_e32 v35, 0xffff0000, v35
	v_lshlrev_b32_e32 v36, 16, v37
	v_and_b32_e32 v37, 0xffff0000, v37
	v_pk_add_f32 v[38:39], v[38:39], v[40:41]
	v_pk_add_f32 v[34:35], v[34:35], v[36:37]
	s_waitcnt vmcnt(0)
	v_pk_fma_f32 v[2:3], v[30:31], v[38:39], v[2:3]
	v_pk_fma_f32 v[4:5], v[32:33], v[34:35], v[4:5]
	global_store_dwordx4 v[52:53], v[2:5], off sc1
	global_load_dwordx2 v[38:39], v[46:47], off offset:512
	global_load_dwordx2 v[40:41], v[48:49], off offset:512
	global_load_dwordx4 v[30:33], v1, s[16:17] offset:1024
	global_load_dwordx4 v[34:37], v[50:51], off offset:1024
	v_mov_b32_e32 v60, v3
	v_mov_b32_e32 v62, v4
	v_mov_b32_e32 v64, v5
	s_waitcnt vmcnt(3)
	v_lshlrev_b32_e32 v42, 16, v38
	v_and_b32_e32 v43, 0xffff0000, v38
	s_waitcnt vmcnt(2)
	v_lshlrev_b32_e32 v44, 16, v40
	v_and_b32_e32 v45, 0xffff0000, v40
	v_lshlrev_b32_e32 v38, 16, v39
	v_and_b32_e32 v39, 0xffff0000, v39
	v_lshlrev_b32_e32 v40, 16, v41
	v_and_b32_e32 v41, 0xffff0000, v41
	v_pk_add_f32 v[42:43], v[42:43], v[44:45]
	v_pk_add_f32 v[38:39], v[38:39], v[40:41]
	s_waitcnt vmcnt(0)
	v_pk_fma_f32 v[30:31], v[34:35], v[42:43], v[30:31]
	v_pk_fma_f32 v[32:33], v[36:37], v[38:39], v[32:33]
	global_store_dwordx4 v[52:53], v[30:33], off offset:1024 sc1
	global_load_dwordx2 v[42:43], v[46:47], off offset:1024
	global_load_dwordx2 v[44:45], v[48:49], off offset:1024
	global_load_dwordx4 v[34:37], v1, s[16:17] offset:2048
	global_load_dwordx4 v[38:41], v[50:51], off offset:2048
	v_mov_b32_e32 v61, v31
	v_pk_mul_f32 v[60:61], v[60:61], v[60:61]
	v_mov_b32_e32 v63, v32
	v_mov_b32_e32 v65, v33
	s_waitcnt vmcnt(3)
	v_lshlrev_b32_e32 v54, 16, v42
	v_and_b32_e32 v55, 0xffff0000, v42
	s_waitcnt vmcnt(2)
	v_lshlrev_b32_e32 v56, 16, v44
	v_and_b32_e32 v57, 0xffff0000, v44
	v_lshlrev_b32_e32 v42, 16, v43
	v_and_b32_e32 v43, 0xffff0000, v43
	v_lshlrev_b32_e32 v44, 16, v45
	v_and_b32_e32 v45, 0xffff0000, v45
	v_pk_add_f32 v[54:55], v[54:55], v[56:57]
	v_pk_add_f32 v[42:43], v[42:43], v[44:45]
	s_waitcnt vmcnt(0)
	v_pk_fma_f32 v[34:35], v[38:39], v[54:55], v[34:35]
	v_pk_fma_f32 v[36:37], v[40:41], v[42:43], v[36:37]
	global_store_dwordx4 v[52:53], v[34:37], off offset:2048 sc1
	global_load_dwordx2 v[54:55], v[46:47], off offset:1536
	global_load_dwordx2 v[56:57], v[48:49], off offset:1536
	global_load_dwordx4 v[38:41], v1, s[16:17] offset:3072
	global_load_dwordx4 v[42:45], v[50:51], off offset:3072
	s_waitcnt vmcnt(3)
	v_lshlrev_b32_e32 v46, 16, v54
	v_and_b32_e32 v47, 0xffff0000, v54
	s_waitcnt vmcnt(2)
	v_lshlrev_b32_e32 v48, 16, v56
	v_and_b32_e32 v49, 0xffff0000, v56
	v_lshlrev_b32_e32 v50, 16, v55
	v_and_b32_e32 v51, 0xffff0000, v55
	v_lshlrev_b32_e32 v54, 16, v57
	v_and_b32_e32 v55, 0xffff0000, v57
	v_pk_add_f32 v[46:47], v[46:47], v[48:49]
	v_pk_add_f32 v[48:49], v[50:51], v[54:55]
	s_waitcnt vmcnt(0)
	v_pk_fma_f32 v[38:39], v[42:43], v[46:47], v[38:39]
	v_pk_fma_f32 v[40:41], v[44:45], v[48:49], v[40:41]
	global_store_dwordx4 v[52:53], v[38:41], off offset:3072 sc1
	global_load_dwordx4 v[42:45], v[6:7], off
	global_load_dwordx4 v[46:49], v[58:59], off
	v_lshl_add_u64 v[54:55], v[24:25], 0, s[14:15]
	global_load_dwordx4 v[50:53], v[54:55], off
	v_mov_b32_e32 v56, v2
	v_mov_b32_e32 v57, v30
	v_pk_fma_f32 v[56:57], v[56:57], v[56:57], v[60:61]
	v_mov_b32_e32 v60, v36
	v_pk_fma_f32 v[56:57], v[62:63], v[62:63], v[56:57]
	v_mov_b32_e32 v62, v34
	v_pk_fma_f32 v[56:57], v[64:65], v[64:65], v[56:57]
	v_mov_b32_e32 v64, v35
	v_mov_b32_e32 v65, v39
	v_mov_b32_e32 v63, v38
	v_pk_mul_f32 v[64:65], v[64:65], v[64:65]
	v_mov_b32_e32 v61, v40
	v_pk_fma_f32 v[62:63], v[62:63], v[62:63], v[64:65]
	v_add_f32_e32 v29, v56, v57
	v_mov_b32_e32 v56, v37
	v_mov_b32_e32 v57, v41
	v_pk_fma_f32 v[60:61], v[60:61], v[60:61], v[62:63]
	s_nop 0
	v_pk_fma_f32 v[56:57], v[56:57], v[56:57], v[60:61]
	s_nop 0
	v_add_f32_e32 v29, v29, v56
	v_add_f32_e32 v29, v29, v57
	s_nop 1
	v_add_f32_dpp v29, v29, v29 quad_perm:[1,0,3,2] row_mask:0xf bank_mask:0xf bound_ctrl:1
	s_nop 1
	v_add_f32_dpp v29, v29, v29 quad_perm:[2,3,0,1] row_mask:0xf bank_mask:0xf bound_ctrl:1
	s_nop 1
	v_add_f32_dpp v29, v29, v29 row_half_mirror row_mask:0xf bank_mask:0xf bound_ctrl:1
	s_nop 1
	v_add_f32_dpp v29, v29, v29 row_mirror row_mask:0xf bank_mask:0xf bound_ctrl:1
	s_nop 0
	v_readlane_b32 s2, v29, 16
	v_readlane_b32 s16, v29, 48
	v_readlane_b32 s14, v29, 0
	v_readlane_b32 s15, v29, 32
	v_mov_b32_e32 v56, s2
	v_mov_b32_e32 v57, s16
	v_pk_add_f32 v[56:57], s[14:15], v[56:57]
	s_nop 0
	v_add_f32_e32 v29, v56, v57
	v_fmamk_f32 v29, v29, 0x3a800000, v28
	v_mul_f32_e32 v56, 0x4b800000, v29
	v_cmp_gt_f32_e32 vcc, s22, v29
	s_nop 1
	v_cndmask_b32_e32 v29, v29, v56, vcc
	v_rsq_f32_e32 v29, v29
	v_lshl_add_u64 v[56:57], v[26:27], 0, s[12:13]
	v_mul_f32_e32 v60, 0x45800000, v29
	v_cndmask_b32_e32 v60, v29, v60, vcc
	v_pk_mul_f32 v[2:3], v[2:3], v[60:61] op_sel_hi:[1,0]
	v_pk_mul_f32 v[4:5], v[4:5], v[60:61] op_sel_hi:[1,0]
	v_pk_mul_f32 v[30:31], v[30:31], v[60:61] op_sel_hi:[1,0]
	v_pk_mul_f32 v[32:33], v[32:33], v[60:61] op_sel_hi:[1,0]
	v_pk_mul_f32 v[34:35], v[34:35], v[60:61] op_sel_hi:[1,0]
	v_pk_mul_f32 v[36:37], v[36:37], v[60:61] op_sel_hi:[1,0]
	v_pk_mul_f32 v[38:39], v[38:39], v[60:61] op_sel_hi:[1,0]
	v_pk_mul_f32 v[40:41], v[40:41], v[60:61] op_sel_hi:[1,0]
	s_waitcnt vmcnt(2)
	v_pk_mul_f32 v[2:3], v[42:43], v[2:3]
	s_waitcnt vmcnt(1)
	v_pk_add_f32 v[42:43], v[46:47], 1.0 op_sel_hi:[1,0]
	v_pk_mul_f32 v[4:5], v[44:45], v[4:5]
	v_pk_add_f32 v[44:45], v[48:49], 1.0 op_sel_hi:[1,0]
	s_waitcnt vmcnt(0)
	v_pk_fma_f32 v[2:3], v[42:43], v[2:3], v[50:51]
	v_pk_fma_f32 v[4:5], v[44:45], v[4:5], v[52:53]
	v_cvt_pk_bf16_f32 v2, v2, v3
	v_cvt_pk_bf16_f32 v3, v4, v5
	global_store_dwordx2 v[56:57], v[2:3], off sc1
	global_load_dwordx4 v[2:5], v[8:9], off
	s_nop 0
	global_load_dwordx4 v[42:45], v[58:59], off offset:1024
	global_load_dwordx4 v[46:49], v[54:55], off offset:1024
	s_waitcnt vmcnt(2)
	v_pk_mul_f32 v[2:3], v[2:3], v[30:31]
	s_waitcnt vmcnt(1)
	v_pk_add_f32 v[30:31], v[42:43], 1.0 op_sel_hi:[1,0]
	v_pk_mul_f32 v[4:5], v[4:5], v[32:33]
	v_pk_add_f32 v[32:33], v[44:45], 1.0 op_sel_hi:[1,0]
	s_waitcnt vmcnt(0)
	v_pk_fma_f32 v[2:3], v[30:31], v[2:3], v[46:47]
	v_pk_fma_f32 v[4:5], v[32:33], v[4:5], v[48:49]
	v_cvt_pk_bf16_f32 v2, v2, v3
	v_cvt_pk_bf16_f32 v3, v4, v5
	global_store_dwordx2 v[56:57], v[2:3], off offset:512 sc1
	global_load_dwordx4 v[2:5], v[10:11], off
	s_nop 0
	global_load_dwordx4 v[30:33], v[58:59], off offset:2048
	global_load_dwordx4 v[42:45], v[54:55], off offset:2048
	s_waitcnt vmcnt(2)
	v_pk_mul_f32 v[2:3], v[2:3], v[34:35]
	s_waitcnt vmcnt(1)
	v_pk_add_f32 v[30:31], v[30:31], 1.0 op_sel_hi:[1,0]
	v_pk_mul_f32 v[4:5], v[4:5], v[36:37]
	v_pk_add_f32 v[32:33], v[32:33], 1.0 op_sel_hi:[1,0]
	s_waitcnt vmcnt(0)
	v_pk_fma_f32 v[2:3], v[2:3], v[30:31], v[42:43]
	v_pk_fma_f32 v[4:5], v[4:5], v[32:33], v[44:45]
	v_cvt_pk_bf16_f32 v2, v2, v3
	v_cvt_pk_bf16_f32 v3, v4, v5
	global_store_dwordx2 v[56:57], v[2:3], off offset:1024 sc1
	global_load_dwordx4 v[2:5], v[12:13], off
	s_nop 0
	global_load_dwordx4 v[30:33], v[58:59], off offset:3072
	global_load_dwordx4 v[34:37], v[54:55], off offset:3072
	s_waitcnt vmcnt(2)
	v_pk_mul_f32 v[2:3], v[38:39], v[2:3]
	s_waitcnt vmcnt(1)
	v_pk_add_f32 v[30:31], v[30:31], 1.0 op_sel_hi:[1,0]
	v_pk_mul_f32 v[4:5], v[40:41], v[4:5]
	v_pk_add_f32 v[32:33], v[32:33], 1.0 op_sel_hi:[1,0]
	s_waitcnt vmcnt(0)
	v_pk_fma_f32 v[2:3], v[2:3], v[30:31], v[34:35]
	v_pk_fma_f32 v[4:5], v[4:5], v[32:33], v[36:37]
	v_cvt_pk_bf16_f32 v2, v2, v3
	v_cvt_pk_bf16_f32 v3, v4, v5
	global_store_dwordx2 v[56:57], v[2:3], off offset:1536 sc1
	s_cbranch_scc0 .LBB0_2462
